# P3 output-gate section: gate/ghead loads of the 3rd and 4th column group issued one group ahead into free registers (copied into place at the old load site)
# speedup vs baseline: 1.0003x; 1.0003x over previous
.LBB0_773:
	s_or_b64 exec, exec, s[0:1]
	s_add_i32 s0, 0, 0x21000
	s_waitcnt lgkmcnt(0)
	s_barrier
	v_lshl_add_u32 v121, v143, 2, s0
	ds_read_b128 v[234:237], v121
	s_waitcnt lgkmcnt(1)
	v_lshlrev_b32_e32 v134, 6, v196
	v_cmp_gt_i32_e64 s[6:7], s86, v132
	v_or_b32_e32 v188, 1, v182
	s_and_b64 s[8:9], s[2:3], s[6:7]
	s_waitcnt lgkmcnt(0)
	v_mul_f32_e32 v48, v48, v234
	v_bfe_u32 v121, v48, 16, 1
	v_mul_f32_e32 v49, v49, v235
	v_add3_u32 v48, v48, v121, s68
	ds_write_b16_d16_hi v222, v48
	v_bfe_u32 v48, v49, 16, 1
	v_add3_u32 v48, v49, v48, s68
	ds_write_b16_d16_hi v225, v48
	v_mul_f32_e32 v48, v50, v236
	v_bfe_u32 v49, v48, 16, 1
	v_add3_u32 v48, v48, v49, s68
	ds_write_b16_d16_hi v229, v48
	v_lshl_add_u32 v48, v113, 2, s0
	ds_read_b128 v[238:241], v48
	v_mul_f32_e32 v48, v51, v237
	v_bfe_u32 v49, v48, 16, 1
	v_add3_u32 v48, v48, v49, s68
	ds_write_b16_d16_hi v211, v48
	s_waitcnt lgkmcnt(1)
	v_mul_f32_e32 v48, v52, v238
	v_bfe_u32 v49, v48, 16, 1
	v_add3_u32 v48, v48, v49, s68
	ds_write_b16_d16_hi v207, v48
	v_mul_f32_e32 v48, v53, v239
	v_bfe_u32 v49, v48, 16, 1
	v_add3_u32 v48, v48, v49, s68
	ds_write_b16_d16_hi v210, v48
	v_mul_f32_e32 v48, v54, v240
	v_bfe_u32 v49, v48, 16, 1
	v_add3_u32 v48, v48, v49, s68
	ds_write_b16_d16_hi v214, v48
	v_lshl_add_u32 v48, v126, 2, s0
	ds_read_b128 v[48:51], v48
	v_mul_f32_e32 v52, v55, v241
	v_bfe_u32 v53, v52, 16, 1
	v_add3_u32 v52, v52, v53, s68
	ds_write_b16_d16_hi v213, v52
	s_waitcnt lgkmcnt(1)
	v_mul_f32_e32 v52, v56, v48
	v_bfe_u32 v53, v52, 16, 1
	v_add3_u32 v52, v52, v53, s68
	ds_write_b16_d16_hi v215, v52
	v_mul_f32_e32 v52, v57, v49
	v_bfe_u32 v53, v52, 16, 1
	v_add3_u32 v52, v52, v53, s68
	ds_write_b16_d16_hi v217, v52
	v_mul_f32_e32 v52, v58, v50
	v_bfe_u32 v53, v52, 16, 1
	v_add3_u32 v52, v52, v53, s68
	ds_write_b16_d16_hi v219, v52
	v_lshl_add_u32 v52, v123, 2, s0
	ds_read_b128 v[52:55], v52
	v_mul_f32_e32 v56, v59, v51
	v_bfe_u32 v57, v56, 16, 1
	v_add3_u32 v56, v56, v57, s68
	ds_write_b16_d16_hi v204, v56
	s_waitcnt lgkmcnt(1)
	v_mul_f32_e32 v56, v60, v52
	v_bfe_u32 v57, v56, 16, 1
	v_add3_u32 v56, v56, v57, s68
	ds_write_b16_d16_hi v202, v56
	v_mul_f32_e32 v56, v61, v53
	v_bfe_u32 v57, v56, 16, 1
	v_add3_u32 v56, v56, v57, s68
	ds_write_b16_d16_hi v203, v56
	v_mul_f32_e32 v56, v62, v54
	v_bfe_u32 v57, v56, 16, 1
	v_add3_u32 v56, v56, v57, s68
	ds_write_b16_d16_hi v205, v56
	v_mul_f32_e32 v56, v63, v55
	v_bfe_u32 v57, v56, 16, 1
	v_add3_u32 v56, v56, v57, s68
	v_mul_f32_e32 v32, v32, v234
	ds_write_b16_d16_hi v206, v56
	v_bfe_u32 v56, v32, 16, 1
	v_add3_u32 v32, v32, v56, s68
	ds_write_b16_d16_hi v208, v32
	v_mul_f32_e32 v32, v33, v235
	v_bfe_u32 v33, v32, 16, 1
	v_add3_u32 v32, v32, v33, s68
	ds_write_b16_d16_hi v209, v32
	v_mul_f32_e32 v32, v34, v236
	v_bfe_u32 v33, v32, 16, 1
	v_add3_u32 v32, v32, v33, s68
	ds_write_b16_d16_hi v212, v32
	v_mul_f32_e32 v32, v35, v237
	v_bfe_u32 v33, v32, 16, 1
	v_add3_u32 v32, v32, v33, s68
	ds_write_b16_d16_hi v216, v32
	v_mul_f32_e32 v32, v36, v238
	v_bfe_u32 v33, v32, 16, 1
	v_add3_u32 v32, v32, v33, s68
	ds_write_b16_d16_hi v218, v32
	v_mul_f32_e32 v32, v37, v239
	v_bfe_u32 v33, v32, 16, 1
	v_add3_u32 v32, v32, v33, s68
	ds_write_b16_d16_hi v220, v32
	v_mul_f32_e32 v32, v38, v240
	v_bfe_u32 v33, v32, 16, 1
	v_add3_u32 v32, v32, v33, s68
	ds_write_b16_d16_hi v221, v32
	v_mul_f32_e32 v32, v39, v241
	v_bfe_u32 v33, v32, 16, 1
	v_add3_u32 v32, v32, v33, s68
	ds_write_b16_d16_hi v223, v32
	v_mul_f32_e32 v32, v40, v48
	v_bfe_u32 v33, v32, 16, 1
	v_add3_u32 v32, v32, v33, s68
	ds_write_b16_d16_hi v224, v32
	v_mul_f32_e32 v32, v41, v49
	v_bfe_u32 v33, v32, 16, 1
	v_add3_u32 v32, v32, v33, s68
	ds_write_b16_d16_hi v226, v32
	v_mul_f32_e32 v32, v42, v50
	v_bfe_u32 v33, v32, 16, 1
	v_add3_u32 v32, v32, v33, s68
	ds_write_b16_d16_hi v227, v32
	v_mul_f32_e32 v32, v43, v51
	v_bfe_u32 v33, v32, 16, 1
	v_add3_u32 v32, v32, v33, s68
	ds_write_b16_d16_hi v228, v32
	v_mul_f32_e32 v32, v44, v52
	v_bfe_u32 v33, v32, 16, 1
	v_add3_u32 v32, v32, v33, s68
	ds_write_b16_d16_hi v230, v32
	v_mul_f32_e32 v32, v45, v53
	v_bfe_u32 v33, v32, 16, 1
	v_add3_u32 v32, v32, v33, s68
	ds_write_b16_d16_hi v231, v32
	v_mul_f32_e32 v32, v46, v54
	v_bfe_u32 v33, v32, 16, 1
	v_add3_u32 v32, v32, v33, s68
	ds_write_b16_d16_hi v232, v32
	v_mul_f32_e32 v32, v47, v55
	v_bfe_u32 v33, v32, 16, 1
	v_add3_u32 v32, v32, v33, s68
	v_ashrrev_i32_e32 v121, 31, v120
	ds_write_b16_d16_hi v233, v32
	v_lshl_add_u64 v[32:33], s[66:67], 0, v[120:121]
	v_lshlrev_b64 v[34:35], 13, v[32:33]
	v_lshl_add_u64 v[38:39], s[52:53], 0, v[34:35]
	s_waitcnt lgkmcnt(0)
	s_barrier
	v_lshl_add_u64 v[34:35], v[38:39], 0, v[134:135]
	global_load_dwordx4 v[40:43], v[34:35], off offset:3072
	v_lshlrev_b32_e32 v121, 7, v196
	global_load_dwordx4 v[48:51], v121, s[18:19]
	ds_read_b128 v[44:47], v117
	ds_read_b128 v[52:55], v191
	ds_read_b128 v[56:59], v190
	ds_read_b128 v[60:63], v161
	global_load_dwordx4 v[200:203], v121, s[18:19] offset:16
	s_waitcnt lgkmcnt(3)
	v_and_b32_e32 v34, 0xffff0000, v46
	v_lshlrev_b32_e32 v35, 16, v46
	v_and_b32_e32 v36, 0xffff0000, v47
	v_lshlrev_b32_e32 v37, 16, v47
	s_waitcnt lgkmcnt(2)
	v_lshlrev_b32_e32 v209, 16, v53
	v_lshlrev_b32_e32 v208, 16, v52
	v_and_b32_e32 v53, 0xffff0000, v53
	v_and_b32_e32 v52, 0xffff0000, v52
	v_pk_mul_f32 v[210:211], v[208:209], v[208:209]
	v_pk_mul_f32 v[212:213], v[52:53], v[52:53]
	v_lshlrev_b32_e32 v221, 16, v55
	v_lshlrev_b32_e32 v220, 16, v54
	v_and_b32_e32 v55, 0xffff0000, v55
	v_and_b32_e32 v54, 0xffff0000, v54
	v_pk_mul_f32 v[222:223], v[220:221], v[220:221]
	v_pk_mul_f32 v[224:225], v[54:55], v[54:55]
	s_waitcnt lgkmcnt(1)
	v_lshlrev_b32_e32 v235, 16, v57
	v_lshlrev_b32_e32 v234, 16, v56
	v_and_b32_e32 v237, 0xffff0000, v57
	v_and_b32_e32 v236, 0xffff0000, v56
	v_pk_mul_f32 v[56:57], v[234:235], v[234:235]
	v_pk_mul_f32 v[238:239], v[236:237], v[236:237]
	v_lshlrev_b32_e32 v241, 16, v59
	v_lshlrev_b32_e32 v240, 16, v58
	v_and_b32_e32 v243, 0xffff0000, v59
	v_and_b32_e32 v242, 0xffff0000, v58
	v_pk_mul_f32 v[58:59], v[240:241], v[240:241]
	v_pk_mul_f32 v[244:245], v[242:243], v[242:243]
	s_waitcnt lgkmcnt(0)
	v_lshlrev_b32_e32 v247, 16, v61
	v_lshlrev_b32_e32 v246, 16, v60
	v_and_b32_e32 v249, 0xffff0000, v61
	v_and_b32_e32 v248, 0xffff0000, v60
	v_pk_mul_f32 v[60:61], v[246:247], v[246:247]
	v_pk_mul_f32 v[250:251], v[248:249], v[248:249]
	v_pk_mul_f32 v[204:205], v[34:35], v[34:35]
	v_pk_mul_f32 v[206:207], v[36:37], v[36:37]
	v_lshlrev_b64 v[32:33], 11, v[32:33]
	v_lshl_add_u64 v[32:33], s[54:55], 0, v[32:33]
	s_waitcnt vmcnt(2)
	v_lshlrev_b32_e32 v46, 16, v40
	v_mul_f32_e32 v47, 0xbfb8aa3b, v46
	v_exp_f32_e32 v136, v47
	v_lshlrev_b32_e32 v47, 16, v41
	v_and_b32_e32 v41, 0xffff0000, v41
	v_and_b32_e32 v40, 0xffff0000, v40
	v_mul_f32_e32 v137, 0xbfb8aa3b, v40
	v_mul_f32_e32 v121, 0xbfb8aa3b, v41
	v_exp_f32_e32 v137, v137
	v_exp_f32_e32 v121, v121
	v_mul_f32_e32 v189, 0xbfb8aa3b, v47
	v_exp_f32_e32 v189, v189
	v_add_f32_e32 v136, 1.0, v136
	v_rcp_f32_e32 v214, v136
	v_add_f32_e32 v136, 1.0, v137
	s_waitcnt vmcnt(1)
	v_mov_b32_e32 v218, v48
	v_add_f32_e32 v48, 1.0, v121
	v_rcp_f32_e32 v216, v136
	v_rcp_f32_e32 v217, v48
	v_add_f32_e32 v121, v210, v212
	v_add_f32_e32 v136, 1.0, v189
	v_add_f32_e32 v121, v211, v121
	v_rcp_f32_e32 v215, v136
	v_add_f32_e32 v121, v213, v121
	v_add_f32_e32 v121, v222, v121
	v_pk_mul_f32 v[40:41], v[216:217], v[40:41]
	v_add_f32_e32 v121, v224, v121
	v_cndmask_b32_e64 v216, v40, v216, s[2:3]
	v_lshlrev_b32_e32 v40, 16, v42
	v_add_f32_e32 v121, v223, v121
	v_pk_mul_f32 v[46:47], v[214:215], v[46:47]
	v_cndmask_b32_e64 v217, v41, v217, s[2:3]
	v_mul_f32_e32 v41, 0xbfb8aa3b, v40
	v_add_f32_e32 v121, v225, v121
	v_cndmask_b32_e64 v214, v46, v214, s[2:3]
	v_exp_f32_e32 v46, v41
	v_lshlrev_b32_e32 v41, 16, v43
	v_add_f32_e32 v56, v56, v121
	v_and_b32_e32 v227, 0xffff0000, v43
	v_mul_f32_e32 v43, 0xbfb8aa3b, v41
	v_add_f32_e32 v56, v238, v56
	v_exp_f32_e32 v43, v43
	v_add_f32_e32 v56, v57, v56
	v_add_f32_e32 v56, v239, v56
	v_add_f32_e32 v56, v58, v56
	v_add_f32_e32 v56, v244, v56
	v_add_f32_e32 v43, 1.0, v43
	v_add_f32_e32 v56, v59, v56
	v_and_b32_e32 v226, 0xffff0000, v42
	v_add_f32_e32 v42, 1.0, v46
	v_rcp_f32_e32 v229, v43
	v_mul_f32_e32 v43, 0xbfb8aa3b, v227
	v_add_f32_e32 v56, v245, v56
	v_rcp_f32_e32 v228, v42
	v_exp_f32_e32 v43, v43
	v_add_f32_e32 v56, v60, v56
	v_add_f32_e32 v56, v250, v56
	v_mov_b32_e32 v219, v50
	v_mov_b32_e32 v50, v49
	v_mul_f32_e32 v42, 0xbfb8aa3b, v226
	v_lshlrev_b32_e32 v49, 16, v63
	v_lshlrev_b32_e32 v48, 16, v62
	v_add_f32_e32 v56, v61, v56
	v_cndmask_b32_e64 v215, v47, v215, s[2:3]
	v_exp_f32_e32 v42, v42
	v_and_b32_e32 v47, 0xffff0000, v63
	v_and_b32_e32 v46, 0xffff0000, v62
	v_pk_mul_f32 v[62:63], v[48:49], v[48:49]
	v_add_f32_e32 v56, v251, v56
	v_pk_mul_f32 v[232:233], v[228:229], v[40:41]
	v_add_f32_e32 v40, 1.0, v43
	v_pk_mul_f32 v[252:253], v[46:47], v[46:47]
	v_add_f32_e32 v56, v62, v56
	v_rcp_f32_e32 v231, v40
	v_lshlrev_b32_e32 v136, 16, v44
	v_and_b32_e32 v40, 0xffff0000, v44
	v_add_f32_e32 v56, v252, v56
	v_lshlrev_b32_e32 v137, 16, v45
	v_and_b32_e32 v41, 0xffff0000, v45
	v_mov_b32_e32 v44, v40
	v_mov_b32_e32 v45, v136
	v_add_f32_e32 v56, v63, v56
	v_add_f32_e32 v42, 1.0, v42
	v_pk_mul_f32 v[44:45], v[44:45], v[44:45]
	v_add_f32_e32 v56, v253, v56
	v_rcp_f32_e32 v230, v42
	v_mov_b32_e32 v42, v41
	v_mov_b32_e32 v43, v137
	v_add_f32_e32 v45, v45, v56
	v_pk_mul_f32 v[42:43], v[42:43], v[42:43]
	v_add_f32_e32 v44, v44, v45
	v_add_f32_e32 v43, v43, v44
	v_add_f32_e32 v42, v42, v43
	v_add_f32_e32 v42, v205, v42
	v_add_f32_e32 v42, v204, v42
	v_add_f32_e32 v42, v207, v42
	v_add_f32_e32 v56, v206, v42
	ds_bpermute_b32 v58, v197, v56
	v_pk_mul_f32 v[44:45], v[230:231], v[226:227]
	s_waitcnt vmcnt(0)
	v_lshlrev_b32_e32 v238, 4, v194
	v_mov_b32_e32 v239, 0
	v_lshl_add_u64 v[244:245], v[38:39], 0, v[238:239]
	global_load_dwordx4 v[210:213], v[244:245], off offset:3072
	v_lshlrev_b32_e32 v238, 5, v194
	global_load_dwordx4 v[222:225], v238, s[18:19]
	global_load_dwordx4 v[250:253], v238, s[18:19] offset:16
	v_mov_b32_e32 v59, v202
	v_cndmask_b32_e64 v57, v45, v231, s[2:3]
	v_cndmask_b32_e64 v43, v233, v229, s[2:3]
	s_waitcnt lgkmcnt(0)
	v_add_f32_e32 v45, v56, v58
	ds_bpermute_b32 v60, v198, v45
	v_cndmask_b32_e64 v56, v44, v230, s[2:3]
	v_mov_b32_e32 v58, v200
	v_cndmask_b32_e64 v42, v232, v228, s[2:3]
	v_mov_b32_e32 v202, v201
	s_waitcnt lgkmcnt(0)
	v_add_f32_e32 v44, v45, v60
	v_fmamk_f32 v44, v44, 0x3c000000, v133
	v_cmp_gt_f32_e32 vcc, s85, v44
	v_mul_f32_e32 v45, 0x4b800000, v44
	v_lshl_add_u64 v[60:61], v[32:33], 0, v[134:135]
	v_cndmask_b32_e32 v44, v44, v45, vcc
	v_rsq_f32_e32 v44, v44
	v_lshlrev_b32_e32 v134, 4, v195
	v_lshl_add_u64 v[62:63], v[38:39], 0, v[134:135]
	v_mul_f32_e32 v45, 0x45800000, v44
	v_cndmask_b32_e32 v44, v44, v45, vcc
	v_pk_mul_f32 v[52:53], v[44:45], v[52:53] op_sel_hi:[0,1]
	v_pk_mul_f32 v[50:51], v[50:51], v[52:53]
	v_pk_mul_f32 v[52:53], v[44:45], v[220:221] op_sel_hi:[0,1]
	v_pk_mul_f32 v[52:53], v[58:59], v[52:53]
	v_pk_mul_f32 v[196:197], v[44:45], v[208:209] op_sel_hi:[0,1]
	v_pk_mul_f32 v[42:43], v[42:43], v[52:53]
	v_pk_mul_f32 v[52:53], v[44:45], v[54:55] op_sel_hi:[0,1]
	v_pk_mul_f32 v[52:53], v[202:203], v[52:53]
	v_pk_mul_f32 v[196:197], v[218:219], v[196:197]
	v_pk_mul_f32 v[50:51], v[216:217], v[50:51]
	v_pk_mul_f32 v[52:53], v[56:57], v[52:53]
	v_pk_mul_f32 v[196:197], v[214:215], v[196:197]
	v_bfe_u32 v45, v53, 16, 1
	v_bfe_u32 v54, v52, 16, 1
	v_bfe_u32 v55, v51, 16, 1
	v_bfe_u32 v56, v50, 16, 1
	v_add3_u32 v50, v50, v56, s68
	v_add3_u32 v51, v51, v55, s68
	v_add3_u32 v52, v52, v54, s68
	v_add3_u32 v45, v53, v45, s68
	v_bfe_u32 v53, v196, 16, 1
	v_bfe_u32 v54, v197, 16, 1
	v_bfe_u32 v55, v42, 16, 1
	v_bfe_u32 v56, v43, 16, 1
	v_add3_u32 v43, v43, v56, s68
	v_add3_u32 v42, v42, v55, s68
	v_add3_u32 v54, v197, v54, s68
	v_add3_u32 v53, v196, v53, s68
	v_lshrrev_b32_e32 v55, 16, v53
	v_lshrrev_b32_e32 v54, 16, v54
	v_lshrrev_b32_e32 v42, 16, v42
	v_lshrrev_b32_e32 v43, 16, v43
	v_and_or_b32 v53, v45, s82, v43
	v_and_or_b32 v52, v52, s82, v42
	v_and_or_b32 v51, v51, s82, v54
	v_and_or_b32 v50, v50, s82, v55
	v_and_b32_e32 v60, 0xffffffc0, v191
	ds_write_b128 v60, v[50:53]
	global_load_dwordx4 v[50:53], v[62:63], off offset:3072
	v_lshlrev_b32_e32 v42, 5, v195
	global_load_dwordx4 v[54:57], v42, s[18:19]
	global_load_dwordx4 v[58:61], v42, s[18:19] offset:16
	v_lshl_add_u64 v[42:43], v[32:33], 0, v[134:135]
	v_lshlrev_b32_e32 v134, 4, v194
	v_lshl_add_u64 v[62:63], v[38:39], 0, v[134:135]
	s_waitcnt vmcnt(2)
	v_lshlrev_b32_e32 v196, 16, v50
	v_and_b32_e32 v50, 0xffff0000, v50
	v_mul_f32_e32 v45, 0xbfb8aa3b, v196
	v_lshlrev_b32_e32 v197, 16, v51
	v_exp_f32_e32 v45, v45
	v_mul_f32_e32 v121, 0xbfb8aa3b, v50
	v_exp_f32_e32 v121, v121
	v_mul_f32_e32 v189, 0xbfb8aa3b, v197
	v_exp_f32_e32 v189, v189
	v_add_f32_e32 v45, 1.0, v45
	v_rcp_f32_e32 v200, v45
	v_add_f32_e32 v45, 1.0, v121
	v_and_b32_e32 v51, 0xffff0000, v51
	v_rcp_f32_e32 v202, v45
	v_add_f32_e32 v45, 1.0, v189
	v_rcp_f32_e32 v201, v45
	v_pk_mul_f32 v[204:205], v[44:45], v[234:235] op_sel_hi:[0,1]
	v_mul_f32_e32 v45, 0xbfb8aa3b, v51
	v_exp_f32_e32 v45, v45
	v_pk_mul_f32 v[196:197], v[200:201], v[196:197]
	v_lshlrev_b32_e32 v198, 16, v52
	s_waitcnt vmcnt(1)
	v_mov_b32_e32 v207, v56
	v_add_f32_e32 v45, 1.0, v45
	v_rcp_f32_e32 v203, v45
	v_cndmask_b32_e64 v197, v197, v201, s[2:3]
	v_cndmask_b32_e64 v196, v196, v200, s[2:3]
	v_pk_mul_f32 v[200:201], v[44:45], v[236:237] op_sel_hi:[0,1]
	v_mov_b32_e32 v56, v55
	v_pk_mul_f32 v[50:51], v[202:203], v[50:51]
	v_and_b32_e32 v52, 0xffff0000, v52
	v_mov_b32_e32 v206, v54
	v_pk_mul_f32 v[54:55], v[56:57], v[200:201]
	v_mul_f32_e32 v45, 0xbfb8aa3b, v198
	v_cndmask_b32_e64 v51, v51, v203, s[2:3]
	v_cndmask_b32_e64 v50, v50, v202, s[2:3]
	v_lshlrev_b32_e32 v199, 16, v53
	v_exp_f32_e32 v45, v45
	v_pk_mul_f32 v[50:51], v[50:51], v[54:55]
	v_mul_f32_e32 v54, 0xbfb8aa3b, v52
	v_exp_f32_e32 v55, v54
	v_mul_f32_e32 v54, 0xbfb8aa3b, v199
	v_exp_f32_e32 v57, v54
	v_add_f32_e32 v45, 1.0, v45
	v_rcp_f32_e32 v54, v45
	v_add_f32_e32 v45, 1.0, v55
	v_and_b32_e32 v53, 0xffff0000, v53
	v_rcp_f32_e32 v56, v45
	v_add_f32_e32 v45, 1.0, v57
	v_rcp_f32_e32 v55, v45
	v_pk_mul_f32 v[200:201], v[44:45], v[240:241] op_sel_hi:[0,1]
	v_mul_f32_e32 v45, 0xbfb8aa3b, v53
	v_exp_f32_e32 v45, v45
	v_pk_mul_f32 v[198:199], v[54:55], v[198:199]
	s_waitcnt vmcnt(0)
	v_lshlrev_b32_e32 v230, 4, v193
	v_mov_b32_e32 v231, 0
	v_lshl_add_u64 v[232:233], v[38:39], 0, v[230:231]
	global_load_dwordx4 v[214:217], v[232:233], off offset:3072
	v_lshlrev_b32_e32 v230, 5, v193
	global_load_dwordx4 v[218:221], v230, s[18:19]
	global_load_dwordx4 v[226:229], v230, s[18:19] offset:16
	v_mov_b32_e32 v203, v60
	v_cndmask_b32_e64 v55, v199, v55, s[2:3]
	v_add_f32_e32 v45, 1.0, v45
	v_rcp_f32_e32 v57, v45
	v_cndmask_b32_e64 v54, v198, v54, s[2:3]
	v_pk_mul_f32 v[198:199], v[44:45], v[242:243] op_sel_hi:[0,1]
	v_mov_b32_e32 v60, v59
	v_pk_mul_f32 v[52:53], v[56:57], v[52:53]
	v_mov_b32_e32 v202, v58
	v_pk_mul_f32 v[58:59], v[60:61], v[198:199]
	v_cndmask_b32_e64 v53, v53, v57, s[2:3]
	v_cndmask_b32_e64 v52, v52, v56, s[2:3]
	v_pk_mul_f32 v[204:205], v[206:207], v[204:205]
	v_pk_mul_f32 v[200:201], v[202:203], v[200:201]
	v_pk_mul_f32 v[52:53], v[52:53], v[58:59]
	v_pk_mul_f32 v[196:197], v[196:197], v[204:205]
	v_pk_mul_f32 v[54:55], v[54:55], v[200:201]
	v_bfe_u32 v45, v53, 16, 1
	v_bfe_u32 v56, v52, 16, 1
	v_bfe_u32 v57, v51, 16, 1
	v_bfe_u32 v58, v50, 16, 1
	v_add3_u32 v50, v50, v58, s68
	v_add3_u32 v51, v51, v57, s68
	v_add3_u32 v52, v52, v56, s68
	v_add3_u32 v45, v53, v45, s68
	v_bfe_u32 v53, v196, 16, 1
	v_bfe_u32 v56, v197, 16, 1
	v_bfe_u32 v57, v54, 16, 1
	v_bfe_u32 v58, v55, 16, 1
	v_add3_u32 v55, v55, v58, s68
	v_add3_u32 v54, v54, v57, s68
	v_add3_u32 v56, v197, v56, s68
	v_add3_u32 v53, v196, v53, s68
	v_lshrrev_b32_e32 v57, 16, v53
	v_lshrrev_b32_e32 v56, 16, v56
	v_lshrrev_b32_e32 v54, 16, v54
	v_lshrrev_b32_e32 v53, 16, v55
	v_and_or_b32 v53, v45, s82, v53
	v_and_or_b32 v52, v52, s82, v54
	v_and_or_b32 v51, v51, s82, v56
	v_and_or_b32 v50, v50, s82, v57
	v_and_b32_e32 v42, 0xffffffc0, v191
	ds_write_b128 v42, v[50:53] offset:16
	v_mov_b32_e32 v50, v210
	v_mov_b32_e32 v51, v211
	v_mov_b32_e32 v52, v212
	v_mov_b32_e32 v53, v213
	v_mov_b32_e32 v54, v222
	v_mov_b32_e32 v55, v223
	v_mov_b32_e32 v56, v224
	v_mov_b32_e32 v57, v225
	v_mov_b32_e32 v58, v250
	v_mov_b32_e32 v59, v251
	v_mov_b32_e32 v60, v252
	v_mov_b32_e32 v61, v253
	v_lshlrev_b32_e32 v42, 5, v194
	v_lshl_add_u64 v[42:43], v[32:33], 0, v[134:135]
	v_lshlrev_b32_e32 v134, 4, v193
	v_lshl_add_u64 v[38:39], v[38:39], 0, v[134:135]
	v_lshl_add_u64 v[32:33], v[32:33], 0, v[134:135]
	v_lshlrev_b32_e32 v62, 16, v50
	v_and_b32_e32 v50, 0xffff0000, v50
	v_mul_f32_e32 v45, 0xbfb8aa3b, v62
	v_lshlrev_b32_e32 v63, 16, v51
	v_exp_f32_e32 v45, v45
	v_mul_f32_e32 v121, 0xbfb8aa3b, v50
	v_exp_f32_e32 v121, v121
	v_mul_f32_e32 v189, 0xbfb8aa3b, v63
	v_exp_f32_e32 v189, v189
	v_add_f32_e32 v45, 1.0, v45
	v_rcp_f32_e32 v196, v45
	v_add_f32_e32 v45, 1.0, v121
	v_and_b32_e32 v51, 0xffff0000, v51
	v_rcp_f32_e32 v198, v45
	v_add_f32_e32 v45, 1.0, v189
	v_rcp_f32_e32 v197, v45
	v_pk_mul_f32 v[200:201], v[44:45], v[246:247] op_sel_hi:[0,1]
	v_mul_f32_e32 v45, 0xbfb8aa3b, v51
	v_exp_f32_e32 v45, v45
	v_pk_mul_f32 v[62:63], v[196:197], v[62:63]
	v_lshlrev_b32_e32 v194, 16, v52
	v_mov_b32_e32 v203, v56
	v_add_f32_e32 v45, 1.0, v45
	v_rcp_f32_e32 v199, v45
	v_cndmask_b32_e64 v63, v63, v197, s[2:3]
	v_cndmask_b32_e64 v62, v62, v196, s[2:3]
	v_pk_mul_f32 v[196:197], v[44:45], v[248:249] op_sel_hi:[0,1]
	v_mov_b32_e32 v56, v55
	v_pk_mul_f32 v[50:51], v[198:199], v[50:51]
	v_and_b32_e32 v52, 0xffff0000, v52
	v_mov_b32_e32 v202, v54
	v_pk_mul_f32 v[54:55], v[56:57], v[196:197]
	v_mul_f32_e32 v45, 0xbfb8aa3b, v194
	v_cndmask_b32_e64 v51, v51, v199, s[2:3]
	v_cndmask_b32_e64 v50, v50, v198, s[2:3]
	v_lshlrev_b32_e32 v195, 16, v53
	v_exp_f32_e32 v45, v45
	v_pk_mul_f32 v[50:51], v[50:51], v[54:55]
	v_mul_f32_e32 v54, 0xbfb8aa3b, v52
	v_exp_f32_e32 v55, v54
	v_mul_f32_e32 v54, 0xbfb8aa3b, v195
	v_exp_f32_e32 v57, v54
	v_add_f32_e32 v45, 1.0, v45
	v_rcp_f32_e32 v54, v45
	v_add_f32_e32 v45, 1.0, v55
	v_and_b32_e32 v53, 0xffff0000, v53
	v_rcp_f32_e32 v56, v45
	v_add_f32_e32 v45, 1.0, v57
	v_rcp_f32_e32 v55, v45
	v_pk_mul_f32 v[48:49], v[44:45], v[48:49] op_sel_hi:[0,1]
	v_mul_f32_e32 v45, 0xbfb8aa3b, v53
	v_exp_f32_e32 v45, v45
	v_mov_b32_e32 v197, v60
	v_mov_b32_e32 v60, v59
	v_mov_b32_e32 v196, v58
	v_add_f32_e32 v45, 1.0, v45
	v_rcp_f32_e32 v57, v45
	v_pk_mul_f32 v[46:47], v[44:45], v[46:47] op_sel_hi:[0,1]
	v_pk_mul_f32 v[194:195], v[54:55], v[194:195]
	v_pk_mul_f32 v[46:47], v[60:61], v[46:47]
	v_pk_mul_f32 v[52:53], v[56:57], v[52:53]
	v_pk_mul_f32 v[200:201], v[202:203], v[200:201]
	v_cndmask_b32_e64 v53, v53, v57, s[2:3]
	v_cndmask_b32_e64 v52, v52, v56, s[2:3]
	v_pk_mul_f32 v[48:49], v[196:197], v[48:49]
	v_cndmask_b32_e64 v55, v195, v55, s[2:3]
	v_cndmask_b32_e64 v54, v194, v54, s[2:3]
	v_pk_mul_f32 v[46:47], v[52:53], v[46:47]
	v_pk_mul_f32 v[62:63], v[62:63], v[200:201]
	v_pk_mul_f32 v[48:49], v[54:55], v[48:49]
	v_bfe_u32 v45, v47, 16, 1
	v_bfe_u32 v52, v46, 16, 1
	v_bfe_u32 v53, v51, 16, 1
	v_bfe_u32 v54, v50, 16, 1
	v_add3_u32 v50, v50, v54, s68
	v_add3_u32 v51, v51, v53, s68
	v_add3_u32 v46, v46, v52, s68
	v_add3_u32 v45, v47, v45, s68
	v_bfe_u32 v47, v62, 16, 1
	v_bfe_u32 v52, v63, 16, 1
	v_bfe_u32 v53, v48, 16, 1
	v_bfe_u32 v54, v49, 16, 1
	v_add3_u32 v49, v49, v54, s68
	v_add3_u32 v48, v48, v53, s68
	v_add3_u32 v52, v63, v52, s68
	v_add3_u32 v47, v62, v47, s68
	v_lshrrev_b32_e32 v53, 16, v47
	v_lshrrev_b32_e32 v47, 16, v52
	v_lshrrev_b32_e32 v48, 16, v48
	v_lshrrev_b32_e32 v49, 16, v49
	v_and_or_b32 v49, v45, s82, v49
	v_and_or_b32 v48, v46, s82, v48
	v_and_or_b32 v47, v51, s82, v47
	v_and_or_b32 v46, v50, s82, v53
	v_and_b32_e32 v42, 0xffffffc0, v191
	ds_write_b128 v42, v[46:49] offset:32
	s_waitcnt vmcnt(0)
	v_mov_b32_e32 v46, v214
	v_mov_b32_e32 v47, v215
	v_mov_b32_e32 v48, v216
	v_mov_b32_e32 v49, v217
	v_mov_b32_e32 v50, v218
	v_mov_b32_e32 v51, v219
	v_mov_b32_e32 v52, v220
	v_mov_b32_e32 v53, v221
	v_mov_b32_e32 v54, v226
	v_mov_b32_e32 v55, v227
	v_mov_b32_e32 v56, v228
	v_mov_b32_e32 v57, v229
	v_lshlrev_b32_e32 v38, 5, v193
	s_waitcnt vmcnt(2)
	v_lshlrev_b32_e32 v38, 16, v46
	v_mul_f32_e32 v39, 0xbfb8aa3b, v38
	v_and_b32_e32 v42, 0xffff0000, v46
	v_exp_f32_e32 v45, v39
	v_lshlrev_b32_e32 v39, 16, v47
	v_mul_f32_e32 v46, 0xbfb8aa3b, v42
	v_and_b32_e32 v43, 0xffff0000, v47
	v_exp_f32_e32 v47, v46
	v_mul_f32_e32 v46, 0xbfb8aa3b, v39
	v_exp_f32_e32 v59, v46
	v_add_f32_e32 v45, 1.0, v45
	v_rcp_f32_e32 v46, v45
	v_add_f32_e32 v45, 1.0, v47
	v_rcp_f32_e32 v58, v45
	v_add_f32_e32 v45, 1.0, v59
	v_rcp_f32_e32 v47, v45
	v_pk_mul_f32 v[60:61], v[44:45], v[136:137] op_sel_hi:[0,1]
	v_mul_f32_e32 v45, 0xbfb8aa3b, v43
	v_exp_f32_e32 v45, v45
	s_waitcnt vmcnt(1)
	v_mov_b32_e32 v63, v52
	v_mov_b32_e32 v52, v51
	v_pk_mul_f32 v[38:39], v[46:47], v[38:39]
	v_add_f32_e32 v45, 1.0, v45
	v_rcp_f32_e32 v59, v45
	v_pk_mul_f32 v[40:41], v[44:45], v[40:41] op_sel_hi:[0,1]
	v_pk_mul_f32 v[40:41], v[52:53], v[40:41]
	v_cndmask_b32_e64 v39, v39, v47, s[2:3]
	v_pk_mul_f32 v[42:43], v[58:59], v[42:43]
	v_cndmask_b32_e64 v38, v38, v46, s[2:3]
	v_cndmask_b32_e64 v43, v43, v59, s[2:3]
	v_cndmask_b32_e64 v42, v42, v58, s[2:3]
	v_pk_mul_f32 v[40:41], v[42:43], v[40:41]
	v_lshlrev_b32_e32 v42, 16, v48
	v_mul_f32_e32 v43, 0xbfb8aa3b, v42
	v_and_b32_e32 v47, 0xffff0000, v49
	v_and_b32_e32 v46, 0xffff0000, v48
	v_exp_f32_e32 v45, v43
	v_lshlrev_b32_e32 v43, 16, v49
	v_mul_f32_e32 v48, 0xbfb8aa3b, v46
	v_mov_b32_e32 v52, v35
	v_mul_f32_e32 v35, 0xbfb8aa3b, v47
	v_exp_f32_e32 v49, v48
	v_mul_f32_e32 v48, 0xbfb8aa3b, v43
	v_exp_f32_e32 v35, v35
	v_exp_f32_e32 v51, v48
	v_add_f32_e32 v45, 1.0, v45
	v_rcp_f32_e32 v48, v45
	v_add_f32_e32 v45, 1.0, v49
	v_add_f32_e32 v35, 1.0, v35
	v_mov_b32_e32 v62, v50
	v_rcp_f32_e32 v50, v45
	v_add_f32_e32 v45, 1.0, v51
	v_rcp_f32_e32 v51, v35
	v_rcp_f32_e32 v49, v45
	v_mov_b32_e32 v35, v36
	v_mov_b32_e32 v53, v37
	s_waitcnt vmcnt(0)
	v_mov_b32_e32 v59, v56
	v_pk_mul_f32 v[34:35], v[44:45], v[34:35] op_sel_hi:[0,1]
	v_mov_b32_e32 v56, v55
	v_pk_mul_f32 v[36:37], v[50:51], v[46:47]
	v_pk_mul_f32 v[52:53], v[44:45], v[52:53] op_sel_hi:[0,1]
	v_mov_b32_e32 v58, v54
	v_pk_mul_f32 v[42:43], v[48:49], v[42:43]
	v_pk_mul_f32 v[34:35], v[56:57], v[34:35]
	v_cndmask_b32_e64 v37, v37, v51, s[2:3]
	v_cndmask_b32_e64 v36, v36, v50, s[2:3]
	v_pk_mul_f32 v[60:61], v[62:63], v[60:61]
	v_pk_mul_f32 v[52:53], v[58:59], v[52:53]
	v_cndmask_b32_e64 v43, v43, v49, s[2:3]
	v_cndmask_b32_e64 v42, v42, v48, s[2:3]
	v_pk_mul_f32 v[34:35], v[36:37], v[34:35]
	v_pk_mul_f32 v[38:39], v[38:39], v[60:61]
	v_pk_mul_f32 v[42:43], v[42:43], v[52:53]
	v_bfe_u32 v36, v35, 16, 1
	v_bfe_u32 v37, v34, 16, 1
	v_bfe_u32 v44, v41, 16, 1
	v_bfe_u32 v45, v40, 16, 1
	v_add3_u32 v40, v40, v45, s68
	v_add3_u32 v41, v41, v44, s68
	v_add3_u32 v34, v34, v37, s68
	v_add3_u32 v35, v35, v36, s68
	v_bfe_u32 v36, v38, 16, 1
	v_bfe_u32 v37, v39, 16, 1
	v_bfe_u32 v44, v42, 16, 1
	v_bfe_u32 v45, v43, 16, 1
	v_add3_u32 v43, v43, v45, s68
	v_add3_u32 v42, v42, v44, s68
	v_add3_u32 v37, v39, v37, s68
	v_add3_u32 v36, v38, v36, s68
	v_lshrrev_b32_e32 v38, 16, v36
	v_lshrrev_b32_e32 v39, 16, v37
	v_lshrrev_b32_e32 v36, 16, v42
	v_lshrrev_b32_e32 v37, 16, v43
	v_and_or_b32 v37, v35, s82, v37
	v_and_or_b32 v36, v34, s82, v36
	v_and_or_b32 v35, v41, s82, v39
	v_and_or_b32 v34, v40, s82, v38
	ds_read_b128 v[42:45], v191 offset:32768
	global_store_dwordx4 v[32:33], v[34:37], off
	v_and_b32_e32 v46, 0xffffffc0, v191
	ds_read_b128 v[50:53], v46
	ds_read_b128 v[54:57], v46 offset:16
	ds_read_b128 v[58:61], v46 offset:32
	s_waitcnt lgkmcnt(0)
	global_store_dwordx4 v[32:33], v[50:53], off offset:-48
	global_store_dwordx4 v[32:33], v[54:57], off offset:-32
	global_store_dwordx4 v[32:33], v[58:61], off offset:-16
	v_add_u32_e32 v32, 0x20c00, v192
	ds_read_b32 v40, v32
	s_waitcnt lgkmcnt(1)
	v_and_b32_e32 v35, 0xffff0000, v43
	v_and_b32_e32 v34, 0xffff0000, v42
	v_and_b32_e32 v39, 0xffff0000, v45
	v_and_b32_e32 v38, 0xffff0000, v44
	v_lshlrev_b32_e32 v33, 16, v43
	v_lshlrev_b32_e32 v32, 16, v42
	s_waitcnt lgkmcnt(0)
	v_pk_mul_f32 v[34:35], v[40:41], v[34:35] op_sel_hi:[0,1]
	v_lshlrev_b32_e32 v37, 16, v45
	v_lshlrev_b32_e32 v36, 16, v44
	v_pk_mul_f32 v[38:39], v[40:41], v[38:39] op_sel_hi:[0,1]
	v_pk_mul_f32 v[32:33], v[40:41], v[32:33] op_sel_hi:[0,1]
	v_pk_mul_f32 v[36:37], v[40:41], v[36:37] op_sel_hi:[0,1]
	v_bfe_u32 v41, v39, 16, 1
	v_bfe_u32 v42, v38, 16, 1
	v_bfe_u32 v43, v35, 16, 1
	v_bfe_u32 v44, v34, 16, 1
	v_add3_u32 v44, v34, v44, s68
	v_add3_u32 v43, v35, v43, s68
	v_add3_u32 v34, v38, v42, s68
	v_add3_u32 v35, v39, v41, s68
	v_bfe_u32 v41, v36, 16, 1
	v_bfe_u32 v42, v37, 16, 1
	v_add3_u32 v37, v37, v42, s68
	v_add3_u32 v36, v36, v41, s68
	v_bfe_u32 v38, v32, 16, 1
	v_bfe_u32 v39, v33, 16, 1
	v_lshrrev_b32_e32 v41, 16, v36
	v_lshrrev_b32_e32 v36, 16, v37
	v_add3_u32 v33, v33, v39, s68
	v_add3_u32 v32, v32, v38, s68
	v_and_or_b32 v35, v35, s82, v36
	ds_read_b128 v[36:39], v190 offset:32768
	v_lshrrev_b32_e32 v32, 16, v32
	v_lshrrev_b32_e32 v33, 16, v33
	v_and_or_b32 v34, v34, s82, v41
	v_and_or_b32 v33, v43, s82, v33
	v_and_or_b32 v32, v44, s82, v32
	ds_write_b128 v191, v[32:35] offset:32768
	s_waitcnt lgkmcnt(1)
	v_lshlrev_b32_e32 v33, 16, v37
	v_lshlrev_b32_e32 v32, 16, v36
	v_and_b32_e32 v35, 0xffff0000, v37
	v_and_b32_e32 v34, 0xffff0000, v36
	v_lshlrev_b32_e32 v37, 16, v39
	v_lshlrev_b32_e32 v36, 16, v38
	v_and_b32_e32 v39, 0xffff0000, v39
	v_and_b32_e32 v38, 0xffff0000, v38
	v_pk_mul_f32 v[34:35], v[40:41], v[34:35] op_sel_hi:[0,1]
	v_pk_mul_f32 v[38:39], v[40:41], v[38:39] op_sel_hi:[0,1]
	v_pk_mul_f32 v[32:33], v[40:41], v[32:33] op_sel_hi:[0,1]
	v_pk_mul_f32 v[36:37], v[40:41], v[36:37] op_sel_hi:[0,1]
	v_bfe_u32 v41, v39, 16, 1
	v_bfe_u32 v42, v38, 16, 1
	v_bfe_u32 v43, v35, 16, 1
	v_bfe_u32 v44, v34, 16, 1
	v_add3_u32 v44, v34, v44, s68
	v_add3_u32 v43, v35, v43, s68
	v_add3_u32 v34, v38, v42, s68
	v_add3_u32 v35, v39, v41, s68
	v_bfe_u32 v41, v36, 16, 1
	v_bfe_u32 v42, v37, 16, 1
	v_add3_u32 v37, v37, v42, s68
	v_add3_u32 v36, v36, v41, s68
	v_bfe_u32 v38, v32, 16, 1
	v_bfe_u32 v39, v33, 16, 1
	v_lshrrev_b32_e32 v41, 16, v36
	v_lshrrev_b32_e32 v36, 16, v37
	v_add3_u32 v33, v33, v39, s68
	v_add3_u32 v32, v32, v38, s68
	v_and_or_b32 v35, v35, s82, v36
	ds_read_b128 v[36:39], v161 offset:32768
	v_lshrrev_b32_e32 v32, 16, v32
	v_lshrrev_b32_e32 v33, 16, v33
	v_and_or_b32 v34, v34, s82, v41
	v_and_or_b32 v33, v43, s82, v33
	v_and_or_b32 v32, v44, s82, v32
	ds_write_b128 v190, v[32:35] offset:32768
	s_waitcnt lgkmcnt(1)
	v_lshlrev_b32_e32 v33, 16, v37
	v_lshlrev_b32_e32 v32, 16, v36
	v_and_b32_e32 v35, 0xffff0000, v37
	v_and_b32_e32 v34, 0xffff0000, v36
	v_pk_mul_f32 v[36:37], v[40:41], v[32:33] op_sel_hi:[0,1]
	v_pk_mul_f32 v[32:33], v[40:41], v[34:35] op_sel_hi:[0,1]
	v_lshlrev_b32_e32 v35, 16, v39
	v_lshlrev_b32_e32 v34, 16, v38
	v_and_b32_e32 v39, 0xffff0000, v39
	v_and_b32_e32 v38, 0xffff0000, v38
	v_pk_mul_f32 v[42:43], v[40:41], v[34:35] op_sel_hi:[0,1]
	v_pk_mul_f32 v[34:35], v[40:41], v[38:39] op_sel_hi:[0,1]
	v_bfe_u32 v38, v35, 16, 1
	v_bfe_u32 v44, v32, 16, 1
	v_bfe_u32 v39, v34, 16, 1
	v_bfe_u32 v41, v33, 16, 1
	v_add3_u32 v32, v32, v44, s68
	v_add3_u32 v35, v35, v38, s68
	v_bfe_u32 v38, v36, 16, 1
	v_bfe_u32 v44, v43, 16, 1
	v_add3_u32 v33, v33, v41, s68
	v_add3_u32 v34, v34, v39, s68
	v_bfe_u32 v39, v37, 16, 1
	v_bfe_u32 v41, v42, 16, 1
	v_add3_u32 v44, v43, v44, s68
	v_add3_u32 v36, v36, v38, s68
	v_add3_u32 v43, v42, v41, s68
	v_add3_u32 v37, v37, v39, s68
	v_lshrrev_b32_e32 v41, 16, v36
	v_lshrrev_b32_e32 v36, 16, v44
	v_lshrrev_b32_e32 v42, 16, v37
	v_and_or_b32 v35, v35, s82, v36
	ds_read_b128 v[36:39], v117 offset:32768
	v_lshrrev_b32_e32 v43, 16, v43
	v_and_or_b32 v34, v34, s82, v43
	v_and_or_b32 v33, v33, s82, v42
	v_and_or_b32 v32, v32, s82, v41
	ds_write_b128 v161, v[32:35] offset:32768
	s_waitcnt lgkmcnt(1)
	v_lshlrev_b32_e32 v33, 16, v37
	v_lshlrev_b32_e32 v32, 16, v36
	v_and_b32_e32 v35, 0xffff0000, v37
	v_and_b32_e32 v34, 0xffff0000, v36
	v_lshlrev_b32_e32 v37, 16, v39
	v_lshlrev_b32_e32 v36, 16, v38
	v_and_b32_e32 v39, 0xffff0000, v39
	v_and_b32_e32 v38, 0xffff0000, v38
	v_pk_mul_f32 v[34:35], v[40:41], v[34:35] op_sel_hi:[0,1]
	v_pk_mul_f32 v[38:39], v[40:41], v[38:39] op_sel_hi:[0,1]
	v_pk_mul_f32 v[32:33], v[40:41], v[32:33] op_sel_hi:[0,1]
	v_pk_mul_f32 v[36:37], v[40:41], v[36:37] op_sel_hi:[0,1]
	v_bfe_u32 v40, v39, 16, 1
	v_bfe_u32 v41, v38, 16, 1
	v_bfe_u32 v42, v35, 16, 1
	v_bfe_u32 v43, v34, 16, 1
	v_add3_u32 v43, v34, v43, s68
	v_add3_u32 v42, v35, v42, s68
	v_add3_u32 v34, v38, v41, s68
	v_add3_u32 v35, v39, v40, s68
	v_bfe_u32 v38, v32, 16, 1
	v_bfe_u32 v39, v33, 16, 1
	v_bfe_u32 v40, v36, 16, 1
	v_bfe_u32 v41, v37, 16, 1
	v_add3_u32 v37, v37, v41, s68
	v_add3_u32 v36, v36, v40, s68
	v_add3_u32 v33, v33, v39, s68
	v_add3_u32 v32, v32, v38, s68
	v_lshrrev_b32_e32 v32, 16, v32
	v_lshrrev_b32_e32 v33, 16, v33
	v_lshrrev_b32_e32 v36, 16, v36
	v_lshrrev_b32_e32 v37, 16, v37
	v_and_or_b32 v35, v35, s82, v37
	v_and_or_b32 v34, v34, s82, v36
	v_and_or_b32 v33, v42, s82, v33
	v_and_or_b32 v32, v43, s82, v32
	ds_write_b128 v117, v[32:35] offset:32768
	s_and_saveexec_b64 s[0:1], s[8:9]
	s_cbranch_execz .LBB0_775
	v_lshl_add_u32 v32, v132, 2, 0
	v_add_u32_e32 v32, 0x20e00, v32
	ds_read_b32 v33, v32
	s_waitcnt lgkmcnt(0)
	v_mul_f32_e32 v33, v109, v33
	ds_write_b32 v32, v33
